# NA attention local block: the four K fragment ds_read_b128 issued as one batch (one LDS round trip instead of two) with counted lgkmcnt waits
# baseline (speedup 1.0000x reference)
.LBB0_2302:
	s_add_i32 s78, s80, s76
	v_cmp_ge_u32_e32 vcc, s78, v141
	v_cmp_le_u32_e64 s[50:51], s78, v143
	s_and_b64 s[50:51], vcc, s[50:51]
	v_mov_b32_e32 v15, v99
	v_mov_b32_e32 v14, v98
	v_mov_b32_e32 v13, v95
	v_mov_b32_e32 v12, v94
	v_mov_b32_e32 v11, v45
	v_mov_b32_e32 v10, v44
	v_mov_b32_e32 v9, v41
	v_mov_b32_e32 v8, v40
	v_mov_b32_e32 v7, v37
	v_mov_b32_e32 v6, v36
	v_mov_b32_e32 v5, v35
	v_mov_b32_e32 v4, v34
	v_mov_b32_e32 v3, v111
	v_mov_b32_e32 v2, v110
	v_mov_b32_e32 v1, v109
	v_mov_b32_e32 v0, v108
	v_mov_b32_e32 v31, v107
	v_mov_b32_e32 v30, v106
	v_mov_b32_e32 v29, v105
	v_mov_b32_e32 v28, v104
	v_mov_b32_e32 v27, v103
	v_mov_b32_e32 v26, v102
	v_mov_b32_e32 v25, v101
	v_mov_b32_e32 v24, v100
	v_mov_b32_e32 v23, v97
	v_mov_b32_e32 v22, v96
	v_mov_b32_e32 v21, v47
	v_mov_b32_e32 v20, v46
	v_mov_b32_e32 v19, v43
	v_mov_b32_e32 v18, v42
	v_mov_b32_e32 v17, v39
	v_mov_b32_e32 v16, v38
	v_mov_b32_e32 v145, v112
	v_mov_b32_e32 v113, v76
	s_and_saveexec_b64 s[76:77], s[50:51]
	s_cbranch_execz .LBB0_2336
	v_add3_u32 v20, s90, v128, v74
	ds_read_b128 v[0:3], v20
	ds_read_b128 v[16:19], v20 offset:32
	ds_read_b128 v[248:251], v20 offset:64
	ds_read_b128 v[252:255], v20 offset:96
	v_cmp_ge_u32_e32 vcc, s78, v142
	v_cmp_lt_u32_e64 s[50:51], s78, v144
	s_and_b64 s[50:51], vcc, s[50:51]
	s_waitcnt lgkmcnt(3)
	v_mfma_f32_32x32x16_bf16 v[0:15], v[0:3], v[48:51], 0
	s_waitcnt lgkmcnt(2)
	v_mfma_f32_32x32x16_bf16 v[0:15], v[16:19], v[52:55], v[0:15]
	s_waitcnt lgkmcnt(1)
	v_mfma_f32_32x32x16_bf16 v[0:15], v[248:251], v[56:59], v[0:15]
	v_mov_b32_e32 v16, 0xff800000
	v_mov_b32_e32 v17, 0xff800000
	s_waitcnt lgkmcnt(0)
	v_mfma_f32_32x32x16_bf16 v[0:15], v[252:255], v[60:63], v[0:15]
	ds_read_b32 v236, v85
	ds_read_b32 v237, v85 offset:4
	ds_read_b32 v238, v85 offset:8
	ds_read_b32 v239, v85 offset:12
	ds_read_b32 v240, v85 offset:32
	ds_read_b32 v241, v85 offset:36
	ds_read_b32 v242, v85 offset:40
	ds_read_b32 v243, v85 offset:44
	ds_read_b32 v244, v85 offset:64
	ds_read_b32 v245, v85 offset:68
	ds_read_b32 v246, v85 offset:72
	ds_read_b32 v247, v85 offset:76
	ds_read_b32 v248, v85 offset:96
	ds_read_b32 v249, v85 offset:100
	ds_read_b32 v250, v85 offset:104
	s_waitcnt lgkmcnt(8)
	ds_read_b32 v251, v85 offset:108
	s_and_b64 s[78:79], s[50:51], s[8:9]
	v_add_f32_e32 v236, v0, v236
	v_cndmask_b32_e64 v17, v140, v236, s[78:79]
	s_andn2_b64 s[78:79], s[50:51], s[10:11]
	v_add_f32_e32 v237, v1, v237
	v_cndmask_b32_e64 v16, v140, v237, s[78:79]
	s_andn2_b64 s[78:79], s[50:51], s[12:13]
	v_add_f32_e32 v238, v2, v238
	v_cndmask_b32_e64 v1, v140, v238, s[78:79]
	s_andn2_b64 s[78:79], s[50:51], s[14:15]
	v_add_f32_e32 v239, v3, v239
	v_cndmask_b32_e64 v0, v140, v239, s[78:79]
	s_andn2_b64 s[78:79], s[50:51], s[16:17]
	v_add_f32_e32 v240, v4, v240
	v_cndmask_b32_e64 v3, v140, v240, s[78:79]
	s_andn2_b64 s[78:79], s[50:51], s[18:19]
	v_add_f32_e32 v241, v5, v241
	v_cndmask_b32_e64 v2, v140, v241, s[78:79]
	s_andn2_b64 s[78:79], s[50:51], s[20:21]
	v_add_f32_e32 v242, v6, v242
	v_cndmask_b32_e64 v5, v140, v242, s[78:79]
	s_waitcnt lgkmcnt(0)
	s_andn2_b64 s[78:79], s[50:51], s[22:23]
	v_add_f32_e32 v243, v7, v243
	v_cndmask_b32_e64 v4, v140, v243, s[78:79]
	s_and_b64 s[78:79], s[50:51], s[24:25]
	v_add_f32_e32 v244, v8, v244
	v_cndmask_b32_e64 v7, v140, v244, s[78:79]
	s_and_b64 s[78:79], s[50:51], s[26:27]
	v_add_f32_e32 v245, v9, v245
	v_cndmask_b32_e64 v6, v140, v245, s[78:79]
	s_andn2_b64 s[78:79], s[50:51], s[28:29]
	v_add_f32_e32 v246, v10, v246
	v_cndmask_b32_e64 v9, v140, v246, s[78:79]
	s_andn2_b64 s[78:79], s[50:51], s[30:31]
	v_add_f32_e32 v247, v11, v247
	v_cndmask_b32_e64 v8, v140, v247, s[78:79]
	s_andn2_b64 s[78:79], s[50:51], s[34:35]
	v_add_f32_e32 v248, v12, v248
	v_cndmask_b32_e64 v11, v140, v248, s[78:79]
	s_andn2_b64 s[78:79], s[50:51], s[36:37]
	v_add_f32_e32 v249, v13, v249
	v_cndmask_b32_e64 v10, v140, v249, s[78:79]
	s_andn2_b64 s[78:79], s[50:51], s[38:39]
	v_add_f32_e32 v250, v14, v250
	v_cndmask_b32_e64 v13, v140, v250, s[78:79]
	s_andn2_b64 s[78:79], s[50:51], s[40:41]
	v_add_f32_e32 v251, v15, v251
	v_cndmask_b32_e64 v12, v140, v251, s[78:79]
	v_max_f32_e32 v14, v16, v16
	v_max_f32_e32 v15, v17, v17
	v_max_f32_e32 v14, v15, v14
	v_max3_f32 v14, v14, v1, v0
	v_max3_f32 v14, v14, v3, v2
	v_max3_f32 v14, v14, v5, v4
	v_max3_f32 v14, v14, v7, v6
	v_max3_f32 v14, v14, v9, v8
	v_max3_f32 v14, v14, v11, v10
	v_max3_f32 v14, v14, v13, v12
	ds_bpermute_b32 v15, v130, v14
	v_add3_u32 v146, s90, v131, v129
	v_add_u32_e32 v162, 0x4800, v146
	ds_read2_b64 v[114:117], v162 offset1:2
	s_waitcnt lgkmcnt(1)
	v_max3_f32 v145, v112, v14, v15
	v_cmp_neq_f32_e32 vcc, s82, v145
	s_nop 1
	v_cndmask_b32_e32 v14, 0, v145, vcc
	v_sub_f32_e32 v0, v0, v14
	v_exp_f32_e32 v123, v0
	v_sub_f32_e32 v0, v3, v14
	v_exp_f32_e32 v150, v0
	v_sub_f32_e32 v0, v2, v14
	v_exp_f32_e32 v151, v0
	v_sub_f32_e32 v0, v5, v14
	v_exp_f32_e32 v152, v0
	v_sub_f32_e32 v0, v4, v14
	v_exp_f32_e32 v153, v0
	v_sub_f32_e32 v0, v7, v14
	v_exp_f32_e32 v154, v0
	v_sub_f32_e32 v0, v6, v14
	v_exp_f32_e32 v155, v0
	v_sub_f32_e32 v0, v9, v14
	v_sub_f32_e32 v15, v112, v14
	v_sub_f32_e32 v17, v17, v14
	v_sub_f32_e32 v16, v16, v14
	v_exp_f32_e32 v156, v0
	v_sub_f32_e32 v0, v8, v14
	v_exp_f32_e32 v33, v17
	v_exp_f32_e32 v113, v16
	v_exp_f32_e32 v157, v0
	v_sub_f32_e32 v0, v11, v14
	v_exp_f32_e32 v32, v15
	v_exp_f32_e32 v158, v0
	v_sub_f32_e32 v0, v10, v14
	v_exp_f32_e32 v159, v0
	v_sub_f32_e32 v0, v13, v14
	v_sub_f32_e32 v1, v1, v14
	v_exp_f32_e32 v160, v0
	v_sub_f32_e32 v0, v12, v14
	v_exp_f32_e32 v122, v1
	v_exp_f32_e32 v161, v0
	v_pk_mul_f32 v[16:17], v[38:39], v[32:33] op_sel_hi:[1,0]
	v_pk_mul_f32 v[18:19], v[42:43], v[32:33] op_sel_hi:[1,0]
	v_pk_mul_f32 v[20:21], v[46:47], v[32:33] op_sel_hi:[1,0]
	v_pk_mul_f32 v[22:23], v[96:97], v[32:33] op_sel_hi:[1,0]
	v_pk_mul_f32 v[24:25], v[100:101], v[32:33] op_sel_hi:[1,0]
	v_pk_mul_f32 v[26:27], v[102:103], v[32:33] op_sel_hi:[1,0]
	v_pk_mul_f32 v[28:29], v[104:105], v[32:33] op_sel_hi:[1,0]
	v_pk_mul_f32 v[30:31], v[106:107], v[32:33] op_sel_hi:[1,0]
	v_pk_mul_f32 v[0:1], v[108:109], v[32:33] op_sel_hi:[1,0]
	v_pk_mul_f32 v[2:3], v[110:111], v[32:33] op_sel_hi:[1,0]
	v_pk_mul_f32 v[4:5], v[34:35], v[32:33] op_sel_hi:[1,0]
	v_pk_mul_f32 v[6:7], v[36:37], v[32:33] op_sel_hi:[1,0]
	v_pk_mul_f32 v[8:9], v[40:41], v[32:33] op_sel_hi:[1,0]
	v_pk_mul_f32 v[10:11], v[44:45], v[32:33] op_sel_hi:[1,0]
	v_pk_mul_f32 v[12:13], v[94:95], v[32:33] op_sel_hi:[1,0]
	v_pk_mul_f32 v[14:15], v[98:99], v[32:33] op_sel_hi:[1,0]
	v_add_f32_e32 v163, 0, v33
	v_cvt_pk_bf16_f32 v118, v33, v113
	v_add_u32_e32 v33, 0x5800, v146
	ds_read2_b64 v[146:149], v33 offset0:64 offset1:66
	v_cvt_pk_bf16_f32 v119, v122, v123
	v_cvt_pk_bf16_f32 v120, v150, v151
	v_cvt_pk_bf16_f32 v121, v152, v153
	v_add_f32_e32 v113, v113, v163
	v_add_f32_e32 v113, v122, v113
	s_waitcnt lgkmcnt(1)
	v_mfma_f32_32x32x16_bf16 v[16:31], v[114:117], v[118:121], v[16:31]
	ds_read2_b64 v[114:117], v162 offset0:4 offset1:6
	v_add_f32_e32 v113, v123, v113
	v_add_f32_e32 v113, v150, v113
	v_add_f32_e32 v113, v151, v113
	v_add_f32_e32 v113, v152, v113
	v_add_f32_e32 v113, v153, v113
	v_add_f32_e32 v113, v154, v113
	s_waitcnt lgkmcnt(1)
	v_mfma_f32_32x32x16_bf16 v[0:15], v[146:149], v[118:121], v[0:15]
	ds_read2_b64 v[146:149], v33 offset0:68 offset1:70
	v_cvt_pk_bf16_f32 v118, v154, v155
	v_cvt_pk_bf16_f32 v119, v156, v157
	v_cvt_pk_bf16_f32 v120, v158, v159
	v_cvt_pk_bf16_f32 v121, v160, v161
	v_add_f32_e32 v33, v155, v113
	v_add_f32_e32 v33, v156, v33
	s_waitcnt lgkmcnt(1)
	v_mfma_f32_32x32x16_bf16 v[16:31], v[114:117], v[118:121], v[16:31]
	v_add_f32_e32 v33, v157, v33
	v_add_f32_e32 v33, v158, v33
	v_add_f32_e32 v33, v159, v33
	v_add_f32_e32 v33, v160, v33
	v_add_f32_e32 v113, v161, v33
	v_fmac_f32_e32 v113, v76, v32
	s_waitcnt lgkmcnt(0)
	v_mfma_f32_32x32x16_bf16 v[0:15], v[146:149], v[118:121], v[0:15]
